# plus: attention softmax subtract/sum with packed f32 ops (32 fewer VALU slots per tile); no attention address trim
# speedup vs baseline: 1.0024x; 1.0024x over previous
.LBB0_582:
	v_pk_add_f32 v[134:135], v[134:135], v[224:225] op_sel_hi:[1,0] neg_lo:[0,1] neg_hi:[0,1]
	v_pk_add_f32 v[136:137], v[136:137], v[224:225] op_sel_hi:[1,0] neg_lo:[0,1] neg_hi:[0,1]
	v_pk_add_f32 v[138:139], v[138:139], v[224:225] op_sel_hi:[1,0] neg_lo:[0,1] neg_hi:[0,1]
	v_pk_add_f32 v[140:141], v[140:141], v[224:225] op_sel_hi:[1,0] neg_lo:[0,1] neg_hi:[0,1]
	v_pk_add_f32 v[234:235], v[146:147], v[224:225] op_sel_hi:[1,0] neg_lo:[0,1] neg_hi:[0,1]
	v_pk_add_f32 v[236:237], v[148:149], v[224:225] op_sel_hi:[1,0] neg_lo:[0,1] neg_hi:[0,1]
	v_pk_add_f32 v[238:239], v[142:143], v[224:225] op_sel_hi:[1,0] neg_lo:[0,1] neg_hi:[0,1]
	v_pk_add_f32 v[244:245], v[144:145], v[224:225] op_sel_hi:[1,0] neg_lo:[0,1] neg_hi:[0,1]
	v_pk_add_f32 v[226:227], v[150:151], v[222:223] op_sel:[0,1] op_sel_hi:[1,1] neg_lo:[0,1] neg_hi:[0,1]
	v_pk_add_f32 v[228:229], v[152:153], v[222:223] op_sel:[0,1] op_sel_hi:[1,1] neg_lo:[0,1] neg_hi:[0,1]
	v_pk_add_f32 v[230:231], v[154:155], v[222:223] op_sel:[0,1] op_sel_hi:[1,1] neg_lo:[0,1] neg_hi:[0,1]
	v_pk_add_f32 v[232:233], v[156:157], v[222:223] op_sel:[0,1] op_sel_hi:[1,1] neg_lo:[0,1] neg_hi:[0,1]
	v_pk_add_f32 v[158:159], v[158:159], v[222:223] op_sel:[0,1] op_sel_hi:[1,1] neg_lo:[0,1] neg_hi:[0,1]
	v_pk_add_f32 v[160:161], v[160:161], v[222:223] op_sel:[0,1] op_sel_hi:[1,1] neg_lo:[0,1] neg_hi:[0,1]
	v_pk_add_f32 v[162:163], v[162:163], v[222:223] op_sel:[0,1] op_sel_hi:[1,1] neg_lo:[0,1] neg_hi:[0,1]
	v_pk_add_f32 v[164:165], v[164:165], v[222:223] op_sel:[0,1] op_sel_hi:[1,1] neg_lo:[0,1] neg_hi:[0,1]
	v_exp_f32_e32 v134, v134
	v_exp_f32_e32 v135, v135
	v_exp_f32_e32 v136, v136
	v_exp_f32_e32 v137, v137
	v_exp_f32_e32 v138, v138
	v_exp_f32_e32 v139, v139
	v_exp_f32_e32 v140, v140
	v_exp_f32_e32 v141, v141
	v_exp_f32_e32 v234, v234
	v_exp_f32_e32 v235, v235
	v_exp_f32_e32 v236, v236
	v_exp_f32_e32 v237, v237
	v_exp_f32_e32 v238, v238
	v_exp_f32_e32 v239, v239
	v_exp_f32_e32 v244, v244
	v_exp_f32_e32 v245, v245
	v_exp_f32_e32 v226, v226
	v_exp_f32_e32 v227, v227
	v_exp_f32_e32 v228, v228
	v_exp_f32_e32 v229, v229
	v_exp_f32_e32 v230, v230
	v_exp_f32_e32 v231, v231
	v_exp_f32_e32 v232, v232
	v_exp_f32_e32 v233, v233
	v_exp_f32_e32 v158, v158
	v_exp_f32_e32 v159, v159
	v_exp_f32_e32 v160, v160
	v_exp_f32_e32 v161, v161
	v_exp_f32_e32 v162, v162
	v_exp_f32_e32 v163, v163
	v_exp_f32_e32 v164, v164
	v_exp_f32_e32 v165, v165
	v_pk_add_f32 v[246:247], v[134:135], v[136:137]
	v_pk_add_f32 v[246:247], v[246:247], v[138:139]
	v_pk_add_f32 v[246:247], v[246:247], v[140:141]
	v_pk_add_f32 v[246:247], v[246:247], v[234:235]
	v_pk_add_f32 v[246:247], v[246:247], v[236:237]
	v_pk_add_f32 v[246:247], v[246:247], v[238:239]
	v_pk_add_f32 v[246:247], v[246:247], v[244:245]
	v_pk_add_f32 v[248:249], v[226:227], v[228:229]
	v_pk_add_f32 v[248:249], v[248:249], v[230:231]
	v_pk_add_f32 v[248:249], v[248:249], v[232:233]
	v_pk_add_f32 v[248:249], v[248:249], v[158:159]
	v_pk_add_f32 v[248:249], v[248:249], v[160:161]
	v_pk_add_f32 v[248:249], v[248:249], v[162:163]
	v_pk_add_f32 v[248:249], v[248:249], v[164:165]
	v_add_f32_e32 v241, v246, v247
	v_fmac_f32_e32 v241, v191, v208
	v_add_f32_e32 v191, v248, v249
	s_mul_i32 s0, s24, 0x4800
	v_fmac_f32_e32 v191, v203, v206
	v_add_u32_e32 v203, s0, v197
	v_cvt_pk_bf16_f32 v154, v158, v159
	v_add_u32_e32 v206, 0xc800, v203
	v_add_u32_e32 v158, 0xd000, v203
	v_cvt_pk_bf16_f32 v155, v160, v161
	v_cvt_pk_bf16_f32 v134, v134, v135
	v_cvt_pk_bf16_f32 v135, v136, v137
	v_cvt_pk_bf16_f32 v136, v138, v139
	v_cvt_pk_bf16_f32 v137, v140, v141
	ds_read2_b64 v[138:141], v206 offset1:4
	ds_read2_b64 v[142:145], v206 offset0:8 offset1:12
	ds_read2_b64 v[146:149], v158 offset0:32 offset1:36
	ds_read2_b64 v[158:161], v158 offset0:40 offset1:44
	v_cvt_pk_bf16_f32 v150, v226, v227
	v_cvt_pk_bf16_f32 v151, v228, v229
	v_cvt_pk_bf16_f32 v152, v230, v231
	v_cvt_pk_bf16_f32 v153, v232, v233
	v_cvt_pk_bf16_f32 v156, v162, v163
	v_cvt_pk_bf16_f32 v157, v164, v165
	v_cvt_pk_bf16_f32 v162, v234, v235
	v_cvt_pk_bf16_f32 v163, v236, v237
	v_cvt_pk_bf16_f32 v164, v238, v239
	v_cvt_pk_bf16_f32 v165, v244, v245
	s_waitcnt lgkmcnt(3)
	v_mfma_f32_16x16x32_bf16 v[62:65], v[138:141], v[150:153], v[62:65]
	v_mfma_f32_16x16x32_bf16 v[30:33], v[138:141], v[134:137], v[30:33]
	s_waitcnt lgkmcnt(2)
	v_mfma_f32_16x16x32_bf16 v[62:65], v[142:145], v[154:157], v[62:65]
	v_mfma_f32_16x16x32_bf16 v[30:33], v[142:145], v[162:165], v[30:33]
	v_add_u32_e32 v142, 0xd800, v203
	ds_read2_b64 v[138:141], v142 offset0:64 offset1:68
	ds_read2_b64 v[142:145], v142 offset0:72 offset1:76
	s_waitcnt lgkmcnt(3)
	v_mfma_f32_16x16x32_bf16 v[58:61], v[146:149], v[150:153], v[58:61]
	v_mfma_f32_16x16x32_bf16 v[26:29], v[146:149], v[134:137], v[26:29]
	s_waitcnt lgkmcnt(2)
	v_mfma_f32_16x16x32_bf16 v[58:61], v[158:161], v[154:157], v[58:61]
	v_mfma_f32_16x16x32_bf16 v[26:29], v[158:161], v[162:165], v[26:29]
	v_add_u32_e32 v158, 0xe000, v203
	ds_read2_b64 v[146:149], v158 offset0:96 offset1:100
	ds_read2_b64 v[158:161], v158 offset0:104 offset1:108
	s_waitcnt lgkmcnt(3)
	v_mfma_f32_16x16x32_bf16 v[54:57], v[138:141], v[150:153], v[54:57]
	v_mfma_f32_16x16x32_bf16 v[22:25], v[138:141], v[134:137], v[22:25]
	s_waitcnt lgkmcnt(2)
	v_mfma_f32_16x16x32_bf16 v[54:57], v[142:145], v[154:157], v[54:57]
	v_mfma_f32_16x16x32_bf16 v[22:25], v[142:145], v[162:165], v[22:25]
	v_add_u32_e32 v142, 0xe800, v203
	ds_read2_b64 v[138:141], v142 offset0:128 offset1:132
	ds_read2_b64 v[142:145], v142 offset0:136 offset1:140
	s_waitcnt lgkmcnt(3)
	v_mfma_f32_16x16x32_bf16 v[50:53], v[146:149], v[150:153], v[50:53]
	v_mfma_f32_16x16x32_bf16 v[18:21], v[146:149], v[134:137], v[18:21]
	s_waitcnt lgkmcnt(2)
	v_mfma_f32_16x16x32_bf16 v[50:53], v[158:161], v[154:157], v[50:53]
	v_mfma_f32_16x16x32_bf16 v[18:21], v[158:161], v[162:165], v[18:21]
	v_add_u32_e32 v158, 0xf000, v203
	ds_read2_b64 v[146:149], v158 offset0:160 offset1:164
	ds_read2_b64 v[158:161], v158 offset0:168 offset1:172
	s_waitcnt lgkmcnt(3)
	v_mfma_f32_16x16x32_bf16 v[46:49], v[138:141], v[150:153], v[46:49]
	v_mfma_f32_16x16x32_bf16 v[14:17], v[138:141], v[134:137], v[14:17]
	s_waitcnt lgkmcnt(2)
	v_mfma_f32_16x16x32_bf16 v[46:49], v[142:145], v[154:157], v[46:49]
	v_mfma_f32_16x16x32_bf16 v[14:17], v[142:145], v[162:165], v[14:17]
	v_add_u32_e32 v142, 0xf800, v203
	ds_read2_b64 v[138:141], v142 offset0:192 offset1:196
	ds_read2_b64 v[142:145], v142 offset0:200 offset1:204
	s_waitcnt lgkmcnt(3)
	v_mfma_f32_16x16x32_bf16 v[42:45], v[146:149], v[150:153], v[42:45]
	v_mfma_f32_16x16x32_bf16 v[10:13], v[146:149], v[134:137], v[10:13]
	s_waitcnt lgkmcnt(2)
	v_mfma_f32_16x16x32_bf16 v[42:45], v[158:161], v[154:157], v[42:45]
	v_mfma_f32_16x16x32_bf16 v[10:13], v[158:161], v[162:165], v[10:13]
	v_add_u32_e32 v158, 0x3800, v206
	ds_read2_b64 v[146:149], v158 offset0:224 offset1:228
	ds_read2_b64 v[158:161], v158 offset0:232 offset1:236
	s_waitcnt lgkmcnt(3)
	v_mfma_f32_16x16x32_bf16 v[38:41], v[138:141], v[150:153], v[38:41]
	v_mfma_f32_16x16x32_bf16 v[6:9], v[138:141], v[134:137], v[6:9]
	s_waitcnt lgkmcnt(2)
	v_mfma_f32_16x16x32_bf16 v[38:41], v[142:145], v[154:157], v[38:41]
	v_mfma_f32_16x16x32_bf16 v[6:9], v[142:145], v[162:165], v[6:9]
	s_waitcnt lgkmcnt(1)
	v_mfma_f32_16x16x32_bf16 v[34:37], v[146:149], v[150:153], v[34:37]
	v_mfma_f32_16x16x32_bf16 v[2:5], v[146:149], v[134:137], v[2:5]
	s_waitcnt lgkmcnt(0)
	v_mfma_f32_16x16x32_bf16 v[34:37], v[158:161], v[154:157], v[34:37]
	v_mfma_f32_16x16x32_bf16 v[2:5], v[158:161], v[162:165], v[2:5]
	v_mov_b32_e32 v203, v191
	v_mov_b32_e32 v191, v241
	s_andn2_b64 vcc, exec, s[6:7]
	s_mov_b64 s[0:1], -1
	s_cbranch_vccz .LBB0_584
	s_branch .LBB0_585
